# v12 + P1b K-loop: compiler-inserted per-iteration s_waitcnt vmcnt(0) (full LDS-DMA drain) hoisted to the loop preheader
# baseline (speedup 1.0000x reference)
.LBB0_696:
	s_ashr_i32 s29, s28, 31
	s_lshl_b64 s[30:31], s[28:29], 20
	s_add_u32 s30, s3, s30
	s_addc_u32 s31, s25, s31
	s_and_b64 s[34:35], s[6:7], exec
	s_cselect_b32 s29, s31, s39
	s_cselect_b32 s68, s30, s38
	s_ashr_i32 s27, s26, 31
	s_lshl_b64 s[34:35], s[26:27], 20
	s_add_u32 s34, s42, s34
	s_addc_u32 s35, s43, s35
	s_and_b64 s[40:41], s[6:7], exec
	s_cselect_b32 s27, s35, s37
	s_cselect_b32 s69, s34, s36
	s_add_u32 s70, s36, 0x100
	s_addc_u32 s71, s37, 0
	s_add_u32 s36, s38, 0x80080
	v_mov_b32_e32 v10, 0
	s_addc_u32 s37, s39, 0
	s_mov_b32 s72, -2
	v_mov_b32_e32 v11, v10
	v_mov_b32_e32 v12, v10
	v_mov_b32_e32 v13, v10
	v_mov_b32_e32 v14, v10
	v_mov_b32_e32 v15, v10
	v_mov_b32_e32 v16, v10
	v_mov_b32_e32 v17, v10
	v_mov_b32_e32 v26, v10
	v_mov_b32_e32 v27, v10
	v_mov_b32_e32 v28, v10
	v_mov_b32_e32 v29, v10
	v_mov_b32_e32 v30, v10
	v_mov_b32_e32 v31, v10
	v_mov_b32_e32 v32, v10
	v_mov_b32_e32 v33, v10
	v_mov_b32_e32 v42, v10
	v_mov_b32_e32 v43, v10
	v_mov_b32_e32 v44, v10
	v_mov_b32_e32 v45, v10
	v_mov_b32_e32 v46, v10
	v_mov_b32_e32 v47, v10
	v_mov_b32_e32 v48, v10
	v_mov_b32_e32 v49, v10
	v_mov_b32_e32 v58, v10
	v_mov_b32_e32 v59, v10
	v_mov_b32_e32 v60, v10
	v_mov_b32_e32 v61, v10
	v_mov_b32_e32 v62, v10
	v_mov_b32_e32 v63, v10
	v_mov_b32_e32 v64, v10
	v_mov_b32_e32 v65, v10
	v_mov_b32_e32 v18, v10
	v_mov_b32_e32 v19, v10
	v_mov_b32_e32 v20, v10
	v_mov_b32_e32 v21, v10
	v_mov_b32_e32 v22, v10
	v_mov_b32_e32 v23, v10
	v_mov_b32_e32 v24, v10
	v_mov_b32_e32 v25, v10
	v_mov_b32_e32 v34, v10
	v_mov_b32_e32 v35, v10
	v_mov_b32_e32 v36, v10
	v_mov_b32_e32 v37, v10
	v_mov_b32_e32 v38, v10
	v_mov_b32_e32 v39, v10
	v_mov_b32_e32 v40, v10
	v_mov_b32_e32 v41, v10
	v_mov_b32_e32 v50, v10
	v_mov_b32_e32 v51, v10
	v_mov_b32_e32 v52, v10
	v_mov_b32_e32 v53, v10
	v_mov_b32_e32 v54, v10
	v_mov_b32_e32 v55, v10
	v_mov_b32_e32 v56, v10
	v_mov_b32_e32 v57, v10
	v_mov_b32_e32 v66, v10
	v_mov_b32_e32 v67, v10
	v_mov_b32_e32 v68, v10
	v_mov_b32_e32 v69, v10
	v_mov_b32_e32 v70, v10
	v_mov_b32_e32 v71, v10
	v_mov_b32_e32 v72, v10
	v_mov_b32_e32 v73, v10
	v_mov_b32_e32 v74, v10
	v_mov_b32_e32 v75, v10
	v_mov_b32_e32 v76, v10
	v_mov_b32_e32 v77, v10
	v_mov_b32_e32 v78, v10
	v_mov_b32_e32 v79, v10
	v_mov_b32_e32 v80, v10
	v_mov_b32_e32 v81, v10
	v_mov_b32_e32 v90, v10
	v_mov_b32_e32 v91, v10
	v_mov_b32_e32 v92, v10
	v_mov_b32_e32 v93, v10
	v_mov_b32_e32 v94, v10
	v_mov_b32_e32 v95, v10
	v_mov_b32_e32 v96, v10
	v_mov_b32_e32 v97, v10
	v_mov_b32_e32 v106, v10
	v_mov_b32_e32 v107, v10
	v_mov_b32_e32 v108, v10
	v_mov_b32_e32 v109, v10
	v_mov_b32_e32 v110, v10
	v_mov_b32_e32 v111, v10
	v_mov_b32_e32 v112, v10
	v_mov_b32_e32 v113, v10
	v_mov_b32_e32 v122, v10
	v_mov_b32_e32 v123, v10
	v_mov_b32_e32 v124, v10
	v_mov_b32_e32 v125, v10
	v_mov_b32_e32 v126, v10
	v_mov_b32_e32 v127, v10
	v_mov_b32_e32 v128, v10
	v_mov_b32_e32 v129, v10
	v_mov_b32_e32 v82, v10
	v_mov_b32_e32 v83, v10
	v_mov_b32_e32 v84, v10
	v_mov_b32_e32 v85, v10
	v_mov_b32_e32 v86, v10
	v_mov_b32_e32 v87, v10
	v_mov_b32_e32 v88, v10
	v_mov_b32_e32 v89, v10
	v_mov_b32_e32 v98, v10
	v_mov_b32_e32 v99, v10
	v_mov_b32_e32 v100, v10
	v_mov_b32_e32 v101, v10
	v_mov_b32_e32 v102, v10
	v_mov_b32_e32 v103, v10
	v_mov_b32_e32 v104, v10
	v_mov_b32_e32 v105, v10
	v_mov_b32_e32 v114, v10
	v_mov_b32_e32 v115, v10
	v_mov_b32_e32 v116, v10
	v_mov_b32_e32 v117, v10
	v_mov_b32_e32 v118, v10
	v_mov_b32_e32 v119, v10
	v_mov_b32_e32 v120, v10
	v_mov_b32_e32 v121, v10
	v_mov_b32_e32 v130, v10
	v_mov_b32_e32 v131, v10
	v_mov_b32_e32 v132, v10
	v_mov_b32_e32 v133, v10
	v_mov_b32_e32 v134, v10
	v_mov_b32_e32 v135, v10
	v_mov_b32_e32 v136, v10
	v_mov_b32_e32 v137, v10
	s_waitcnt vmcnt(0)
.LBB0_697:
	s_waitcnt lgkmcnt(0)
	ds_read_b128 v[2:5], v188
	ds_read_b128 v[6:9], v188 offset:1024
	ds_read_b128 v[138:141], v188 offset:2048
	ds_read_b128 v[142:145], v188 offset:3072
	ds_read_b128 v[146:149], v189
	ds_read_b128 v[150:153], v189 offset:1024
	ds_read_b128 v[172:175], v189 offset:2048
	ds_read_b128 v[176:179], v189 offset:3072
	s_add_u32 s38, s36, 0xfff80080
	s_addc_u32 s39, s37, -1
	s_cmp_eq_u32 s72, 28
	s_cselect_b32 s41, s29, s39
	s_cselect_b32 s40, s68, s38
	s_cselect_b32 s39, s27, s71
	s_cselect_b32 s38, s69, s70
	s_add_i32 m0, s9, 0xc000
	ds_read_b128 v[192:195], v190
	ds_read_b128 v[196:199], v190 offset:1024
	ds_read_b128 v[200:203], v190 offset:2048
	ds_read_b128 v[204:207], v190 offset:3072
	ds_read_b128 v[208:211], v190 offset:4096
	ds_read_b128 v[212:215], v190 offset:5120
	ds_read_b128 v[216:219], v190 offset:6144
	ds_read_b128 v[220:223], v190 offset:7168
	global_load_lds_dwordx4 v166, s[36:37]
	s_add_i32 m0, s9, 0xe000
	s_nop 0
	global_load_lds_dwordx4 v164, s[36:37]
	s_waitcnt vmcnt(8)
	s_waitcnt lgkmcnt(0)
	s_setprio 1
	s_barrier
	v_mfma_i32_16x16x64_i8 v[134:137], v[2:5], v[192:195], v[134:137]
	v_mfma_i32_16x16x64_i8 v[130:133], v[138:141], v[192:195], v[130:133]
	v_mfma_i32_16x16x64_i8 v[118:121], v[2:5], v[200:203], v[118:121]
	v_mfma_i32_16x16x64_i8 v[114:117], v[138:141], v[200:203], v[114:117]
	v_mfma_i32_16x16x64_i8 v[102:105], v[2:5], v[208:211], v[102:105]
	v_mfma_i32_16x16x64_i8 v[98:101], v[138:141], v[208:211], v[98:101]
	v_mfma_i32_16x16x64_i8 v[86:89], v[2:5], v[216:219], v[86:89]
	v_mfma_i32_16x16x64_i8 v[82:85], v[138:141], v[216:219], v[82:85]
	v_mfma_i32_16x16x64_i8 v[134:137], v[6:9], v[196:199], v[134:137]
	v_mfma_i32_16x16x64_i8 v[130:133], v[142:145], v[196:199], v[130:133]
	v_mfma_i32_16x16x64_i8 v[118:121], v[6:9], v[204:207], v[118:121]
	v_mfma_i32_16x16x64_i8 v[114:117], v[142:145], v[204:207], v[114:117]
	v_mfma_i32_16x16x64_i8 v[102:105], v[6:9], v[212:215], v[102:105]
	v_mfma_i32_16x16x64_i8 v[98:101], v[142:145], v[212:215], v[98:101]
	v_mfma_i32_16x16x64_i8 v[86:89], v[6:9], v[220:223], v[86:89]
	v_mfma_i32_16x16x64_i8 v[82:85], v[142:145], v[220:223], v[82:85]
	v_mfma_i32_16x16x64_i8 v[126:129], v[146:149], v[192:195], v[126:129]
	v_mfma_i32_16x16x64_i8 v[122:125], v[172:175], v[192:195], v[122:125]
	v_mfma_i32_16x16x64_i8 v[110:113], v[146:149], v[200:203], v[110:113]
	v_mfma_i32_16x16x64_i8 v[106:109], v[172:175], v[200:203], v[106:109]
	v_mfma_i32_16x16x64_i8 v[94:97], v[146:149], v[208:211], v[94:97]
	v_mfma_i32_16x16x64_i8 v[90:93], v[172:175], v[208:211], v[90:93]
	v_mfma_i32_16x16x64_i8 v[78:81], v[146:149], v[216:219], v[78:81]
	v_mfma_i32_16x16x64_i8 v[74:77], v[172:175], v[216:219], v[74:77]
	v_mfma_i32_16x16x64_i8 v[126:129], v[150:153], v[196:199], v[126:129]
	v_mfma_i32_16x16x64_i8 v[122:125], v[176:179], v[196:199], v[122:125]
	v_mfma_i32_16x16x64_i8 v[110:113], v[150:153], v[204:207], v[110:113]
	v_mfma_i32_16x16x64_i8 v[106:109], v[176:179], v[204:207], v[106:109]
	v_mfma_i32_16x16x64_i8 v[94:97], v[150:153], v[212:215], v[94:97]
	v_mfma_i32_16x16x64_i8 v[90:93], v[176:179], v[212:215], v[90:93]
	v_mfma_i32_16x16x64_i8 v[78:81], v[150:153], v[220:223], v[78:81]
	v_mfma_i32_16x16x64_i8 v[74:77], v[176:179], v[220:223], v[74:77]
	s_barrier
	s_setprio 0
	s_add_i32 s73, s65, s44
	v_lshl_add_u64 v[180:181], s[38:39], 0, v[158:159]
	s_mov_b32 m0, s73
	ds_read_b128 v[192:195], v190 offset:16384
	ds_read_b128 v[196:199], v190 offset:17408
	ds_read_b128 v[200:203], v190 offset:18432
	ds_read_b128 v[204:207], v190 offset:19456
	ds_read_b128 v[208:211], v190 offset:20480
	ds_read_b128 v[212:215], v190 offset:21504
	ds_read_b128 v[216:219], v190 offset:22528
	ds_read_b128 v[220:223], v190 offset:23552
	global_load_lds_dwordx4 v[180:181], off
	s_add_i32 m0, s73, 0x2000
	s_add_u32 s76, s38, 0x80000
	v_lshl_add_u64 v[224:225], s[38:39], 0, v[154:155]
	s_addc_u32 s77, s39, 0
	s_add_i32 s73, s66, s44
	global_load_lds_dwordx4 v[224:225], off
	s_mov_b32 m0, s73
	v_lshl_add_u64 v[228:229], s[40:41], 0, v[156:157]
	global_load_lds_dwordx4 v158, s[76:77]
	s_add_i32 m0, s73, 0x2000
	s_nop 0
	global_load_lds_dwordx4 v154, s[76:77]
	v_lshl_add_u64 v[226:227], s[40:41], 0, v[160:161]
	s_mov_b32 m0, s9
	s_nop 0
	global_load_lds_dwordx4 v[226:227], off
	s_mov_b32 m0, s47
	s_nop 0
	global_load_lds_dwordx4 v[228:229], off
	s_waitcnt vmcnt(8)
	s_waitcnt lgkmcnt(0)
	s_setprio 1
	s_barrier
	v_mfma_i32_16x16x64_i8 v[70:73], v[2:5], v[192:195], v[70:73]
	v_mfma_i32_16x16x64_i8 v[66:69], v[138:141], v[192:195], v[66:69]
	v_mfma_i32_16x16x64_i8 v[54:57], v[2:5], v[200:203], v[54:57]
	v_mfma_i32_16x16x64_i8 v[50:53], v[138:141], v[200:203], v[50:53]
	v_mfma_i32_16x16x64_i8 v[38:41], v[2:5], v[208:211], v[38:41]
	v_mfma_i32_16x16x64_i8 v[34:37], v[138:141], v[208:211], v[34:37]
	v_mfma_i32_16x16x64_i8 v[2:5], v[2:5], v[216:219], v[22:25]
	v_mfma_i32_16x16x64_i8 v[70:73], v[6:9], v[196:199], v[70:73]
	v_mfma_i32_16x16x64_i8 v[66:69], v[142:145], v[196:199], v[66:69]
	v_mfma_i32_16x16x64_i8 v[54:57], v[6:9], v[204:207], v[54:57]
	v_mfma_i32_16x16x64_i8 v[50:53], v[142:145], v[204:207], v[50:53]
	v_mfma_i32_16x16x64_i8 v[38:41], v[6:9], v[212:215], v[38:41]
	v_mfma_i32_16x16x64_i8 v[34:37], v[142:145], v[212:215], v[34:37]
	v_mfma_i32_16x16x64_i8 v[2:5], v[6:9], v[220:223], v[2:5]
	v_mfma_i32_16x16x64_i8 v[6:9], v[138:141], v[216:219], v[18:21]
	v_mfma_i32_16x16x64_i8 v[6:9], v[142:145], v[220:223], v[6:9]
	v_mfma_i32_16x16x64_i8 v[18:21], v[146:149], v[192:195], v[62:65]
	v_mfma_i32_16x16x64_i8 v[62:65], v[150:153], v[196:199], v[18:21]
	v_mfma_i32_16x16x64_i8 v[18:21], v[172:175], v[192:195], v[58:61]
	v_mfma_i32_16x16x64_i8 v[58:61], v[176:179], v[196:199], v[18:21]
	v_mfma_i32_16x16x64_i8 v[18:21], v[146:149], v[200:203], v[46:49]
	v_mfma_i32_16x16x64_i8 v[46:49], v[150:153], v[204:207], v[18:21]
	v_mfma_i32_16x16x64_i8 v[18:21], v[172:175], v[200:203], v[42:45]
	v_mfma_i32_16x16x64_i8 v[42:45], v[176:179], v[204:207], v[18:21]
	v_mfma_i32_16x16x64_i8 v[18:21], v[146:149], v[208:211], v[30:33]
	v_mfma_i32_16x16x64_i8 v[30:33], v[150:153], v[212:215], v[18:21]
	v_mfma_i32_16x16x64_i8 v[18:21], v[172:175], v[208:211], v[26:29]
	v_mfma_i32_16x16x64_i8 v[14:17], v[146:149], v[216:219], v[14:17]
	v_mfma_i32_16x16x64_i8 v[10:13], v[172:175], v[216:219], v[10:13]
	v_mfma_i32_16x16x64_i8 v[26:29], v[176:179], v[212:215], v[18:21]
	v_mfma_i32_16x16x64_i8 v[14:17], v[150:153], v[220:223], v[14:17]
	v_mfma_i32_16x16x64_i8 v[10:13], v[176:179], v[220:223], v[10:13]
	s_barrier
	s_setprio 0
	s_add_i32 s73, 0, 0x18000
	s_add_i32 s75, 0, 0x1c000
	v_add_u32_e32 v142, s73, v182
	v_add_u32_e32 v162, s75, v182
	ds_read_b128 v[18:21], v142
	ds_read_b128 v[22:25], v142 offset:1024
	ds_read_b128 v[138:141], v142 offset:2048
	ds_read_b128 v[142:145], v142 offset:3072
	ds_read_b128 v[146:149], v162
	ds_read_b128 v[150:153], v162 offset:1024
	ds_read_b128 v[172:175], v162 offset:2048
	ds_read_b128 v[176:179], v162 offset:3072
	s_add_u32 s40, s40, 0x80000
	s_addc_u32 s41, s41, 0
	s_mov_b32 m0, s49
	ds_read_b128 v[192:195], v190 offset:32768
	ds_read_b128 v[196:199], v190 offset:33792
	ds_read_b128 v[200:203], v190 offset:34816
	ds_read_b128 v[204:207], v190 offset:35840
	ds_read_b128 v[208:211], v190 offset:36864
	ds_read_b128 v[212:215], v190 offset:37888
	ds_read_b128 v[216:219], v190 offset:38912
	ds_read_b128 v[220:223], v190 offset:39936
	global_load_lds_dwordx4 v160, s[40:41]
	s_mov_b32 m0, s60
	s_nop 0
	global_load_lds_dwordx4 v156, s[40:41]
	s_waitcnt vmcnt(8)
	s_waitcnt lgkmcnt(0)
	s_setprio 1
	s_barrier
	v_mfma_i32_16x16x64_i8 v[134:137], v[18:21], v[192:195], v[134:137]
	v_mfma_i32_16x16x64_i8 v[130:133], v[138:141], v[192:195], v[130:133]
	v_mfma_i32_16x16x64_i8 v[118:121], v[18:21], v[200:203], v[118:121]
	v_mfma_i32_16x16x64_i8 v[114:117], v[138:141], v[200:203], v[114:117]
	v_mfma_i32_16x16x64_i8 v[102:105], v[18:21], v[208:211], v[102:105]
	v_mfma_i32_16x16x64_i8 v[98:101], v[138:141], v[208:211], v[98:101]
	v_mfma_i32_16x16x64_i8 v[86:89], v[18:21], v[216:219], v[86:89]
	v_mfma_i32_16x16x64_i8 v[82:85], v[138:141], v[216:219], v[82:85]
	v_mfma_i32_16x16x64_i8 v[134:137], v[22:25], v[196:199], v[134:137]
	v_mfma_i32_16x16x64_i8 v[130:133], v[142:145], v[196:199], v[130:133]
	v_mfma_i32_16x16x64_i8 v[118:121], v[22:25], v[204:207], v[118:121]
	v_mfma_i32_16x16x64_i8 v[114:117], v[142:145], v[204:207], v[114:117]
	v_mfma_i32_16x16x64_i8 v[102:105], v[22:25], v[212:215], v[102:105]
	v_mfma_i32_16x16x64_i8 v[98:101], v[142:145], v[212:215], v[98:101]
	v_mfma_i32_16x16x64_i8 v[86:89], v[22:25], v[220:223], v[86:89]
	v_mfma_i32_16x16x64_i8 v[82:85], v[142:145], v[220:223], v[82:85]
	v_mfma_i32_16x16x64_i8 v[126:129], v[146:149], v[192:195], v[126:129]
	v_mfma_i32_16x16x64_i8 v[122:125], v[172:175], v[192:195], v[122:125]
	v_mfma_i32_16x16x64_i8 v[110:113], v[146:149], v[200:203], v[110:113]
	v_mfma_i32_16x16x64_i8 v[106:109], v[172:175], v[200:203], v[106:109]
	v_mfma_i32_16x16x64_i8 v[94:97], v[146:149], v[208:211], v[94:97]
	v_mfma_i32_16x16x64_i8 v[90:93], v[172:175], v[208:211], v[90:93]
	v_mfma_i32_16x16x64_i8 v[78:81], v[146:149], v[216:219], v[78:81]
	v_mfma_i32_16x16x64_i8 v[74:77], v[172:175], v[216:219], v[74:77]
	v_mfma_i32_16x16x64_i8 v[126:129], v[150:153], v[196:199], v[126:129]
	v_mfma_i32_16x16x64_i8 v[122:125], v[176:179], v[196:199], v[122:125]
	v_mfma_i32_16x16x64_i8 v[110:113], v[150:153], v[204:207], v[110:113]
	v_mfma_i32_16x16x64_i8 v[106:109], v[176:179], v[204:207], v[106:109]
	v_mfma_i32_16x16x64_i8 v[94:97], v[150:153], v[212:215], v[94:97]
	v_mfma_i32_16x16x64_i8 v[90:93], v[176:179], v[212:215], v[90:93]
	v_mfma_i32_16x16x64_i8 v[78:81], v[150:153], v[220:223], v[78:81]
	v_mfma_i32_16x16x64_i8 v[74:77], v[176:179], v[220:223], v[74:77]
	s_barrier
	s_setprio 0
	s_add_i32 s40, s73, s44
	v_lshl_add_u64 v[180:181], v[180:181], 0, s[20:21]
	s_mov_b32 m0, s40
	ds_read_b128 v[192:195], v190 offset:49152
	ds_read_b128 v[196:199], v190 offset:50176
	ds_read_b128 v[200:203], v190 offset:51200
	ds_read_b128 v[204:207], v190 offset:52224
	ds_read_b128 v[208:211], v190 offset:53248
	ds_read_b128 v[212:215], v190 offset:54272
	ds_read_b128 v[216:219], v190 offset:55296
	ds_read_b128 v[220:223], v190 offset:56320
	global_load_lds_dwordx4 v[180:181], off
	s_add_i32 m0, s40, 0x2000
	s_add_u32 s38, s38, 0x80080
	v_lshl_add_u64 v[180:181], v[224:225], 0, s[20:21]
	s_addc_u32 s39, s39, 0
	s_add_i32 s40, s75, s44
	global_load_lds_dwordx4 v[180:181], off
	s_mov_b32 m0, s40
	s_nop 0
	global_load_lds_dwordx4 v158, s[38:39]
	s_add_i32 m0, s40, 0x2000
	s_nop 0
	global_load_lds_dwordx4 v154, s[38:39]
	v_lshl_add_u64 v[180:181], v[226:227], 0, s[20:21]
	s_mov_b32 m0, s62
	s_nop 0
	global_load_lds_dwordx4 v[180:181], off
	v_lshl_add_u64 v[180:181], v[228:229], 0, s[20:21]
	s_mov_b32 m0, s63
	s_nop 0
	global_load_lds_dwordx4 v[180:181], off
	s_waitcnt vmcnt(8)
	s_waitcnt lgkmcnt(0)
	s_setprio 1
	s_barrier
	v_mfma_i32_16x16x64_i8 v[70:73], v[18:21], v[192:195], v[70:73]
	v_mfma_i32_16x16x64_i8 v[54:57], v[18:21], v[200:203], v[54:57]
	v_mfma_i32_16x16x64_i8 v[38:41], v[18:21], v[208:211], v[38:41]
	v_mfma_i32_16x16x64_i8 v[2:5], v[18:21], v[216:219], v[2:5]
	v_mfma_i32_16x16x64_i8 v[70:73], v[22:25], v[196:199], v[70:73]
	v_mfma_i32_16x16x64_i8 v[66:69], v[138:141], v[192:195], v[66:69]
	v_mfma_i32_16x16x64_i8 v[54:57], v[22:25], v[204:207], v[54:57]
	v_mfma_i32_16x16x64_i8 v[50:53], v[138:141], v[200:203], v[50:53]
	v_mfma_i32_16x16x64_i8 v[38:41], v[22:25], v[212:215], v[38:41]
	v_mfma_i32_16x16x64_i8 v[34:37], v[138:141], v[208:211], v[34:37]
	v_mfma_i32_16x16x64_i8 v[22:25], v[22:25], v[220:223], v[2:5]
	v_mfma_i32_16x16x64_i8 v[2:5], v[138:141], v[216:219], v[6:9]
	v_mfma_i32_16x16x64_i8 v[66:69], v[142:145], v[196:199], v[66:69]
	v_mfma_i32_16x16x64_i8 v[50:53], v[142:145], v[204:207], v[50:53]
	v_mfma_i32_16x16x64_i8 v[34:37], v[142:145], v[212:215], v[34:37]
	v_mfma_i32_16x16x64_i8 v[18:21], v[142:145], v[220:223], v[2:5]
	v_mfma_i32_16x16x64_i8 v[2:5], v[146:149], v[192:195], v[62:65]
	v_mfma_i32_16x16x64_i8 v[62:65], v[150:153], v[196:199], v[2:5]
	v_mfma_i32_16x16x64_i8 v[2:5], v[172:175], v[192:195], v[58:61]
	v_mfma_i32_16x16x64_i8 v[58:61], v[176:179], v[196:199], v[2:5]
	v_mfma_i32_16x16x64_i8 v[2:5], v[146:149], v[200:203], v[46:49]
	v_mfma_i32_16x16x64_i8 v[46:49], v[150:153], v[204:207], v[2:5]
	v_mfma_i32_16x16x64_i8 v[2:5], v[172:175], v[200:203], v[42:45]
	v_mfma_i32_16x16x64_i8 v[42:45], v[176:179], v[204:207], v[2:5]
	v_mfma_i32_16x16x64_i8 v[2:5], v[146:149], v[208:211], v[30:33]
	v_mfma_i32_16x16x64_i8 v[30:33], v[150:153], v[212:215], v[2:5]
	v_mfma_i32_16x16x64_i8 v[2:5], v[172:175], v[208:211], v[26:29]
	v_mfma_i32_16x16x64_i8 v[26:29], v[176:179], v[212:215], v[2:5]
	v_mfma_i32_16x16x64_i8 v[2:5], v[146:149], v[216:219], v[14:17]
	v_mfma_i32_16x16x64_i8 v[14:17], v[150:153], v[220:223], v[2:5]
	v_mfma_i32_16x16x64_i8 v[2:5], v[172:175], v[216:219], v[10:13]
	v_mfma_i32_16x16x64_i8 v[10:13], v[176:179], v[220:223], v[2:5]
	s_barrier
	s_setprio 0
	s_add_i32 s72, s72, 2
	s_add_u32 s70, s70, 0x100
	s_addc_u32 s71, s71, 0
	s_add_u32 s36, s36, 0x100
	s_addc_u32 s37, s37, 0
	s_cmp_gt_u32 s72, 29
	s_cbranch_scc0 .LBB0_697
	s_and_b64 vcc, exec, s[22:23]
	s_cbranch_vccz .LBB0_700
	s_barrier
